# NSA fast paths: last QK MFMA writes the new score tile directly into the pending registers v[16:31] (moved after their last softmax read); the 8 v_mov_b64 copies per step removed
# speedup vs baseline: 1.0169x; 1.0101x over previous
; #define LAS __attribute__((address_space(3)))
; DI float xh_sum(float x) { const unsigned u = __float_as_uint(x); const auto r = __builtin_amdgcn_permlane32_swap(u, u, false, false); return __uint_as_float(r[0]) + __uint_as_float(r[1]); }
; #define MFMA32(a, b, c) __builtin_amdgcn_mfma_f32_32x32x16_bf16((a), (b), (c), 0, 0, 0)
; DI bf16x8 cat44(s16x4 a, s16x4 b) { return __builtin_shufflevector(a, b, 0, 1, 2, 3, 4, 5, 6, 7); }
; template <int MODE>
; DI void co_finish(f32x16 S, LAS unsigned char* st, int key_base, AttnState& as, int tq, bool rowsel, int vb_in, int hh) {
;     ...
;     const float mxs = mx * SM_SCALE; const bool need = mxs > as.m + 8.f;
;     const float mnew = need ? mxs : as.m, muse = -fmaxf(mnew, -1e20f); float ps = 0.f;
; #pragma unroll
;     for (int i = 0; i < 16; ++i) { const float p = __builtin_amdgcn_exp2f(__builtin_fmaf(S[i], SM_SCALE, muse)); S[i] = p; ps += p; }
;     ps = xh_sum(ps);
;     if (__builtin_amdgcn_ballot_w64(need) != 0ull) {
;         const float alpha = __builtin_amdgcn_exp2f(as.m - mnew);
;         as.l *= alpha;
; #pragma unroll
;         for (int dt = 0; dt < 4; ++dt)
; #pragma unroll
;             for (int i = 0; i < 16; ++i) as.acc[dt][i] *= alpha;
;     }
;     as.l += ps; as.m = mnew;
;     const bf16x8 p0 = pack8(S, 0), p1 = pack8(S, 1);
;     __builtin_amdgcn_s_setprio(1);
; #pragma unroll
;     for (int dt = 0; dt < 4; ++dt) {
;         LAS unsigned char* vp = st + 2048 * dt;
;         const bf16x8 a0 = cat44(*(const LAS s16x4*)(vp + (vb ^ 0)), *(const LAS s16x4*)(vp + (vb ^ 16))), a1 = cat44(*(const LAS s16x4*)(vp + (vb ^ 32)), *(const LAS s16x4*)(vp + (vb ^ 48)));
;         as.acc[dt] = MFMA32(a0, p0, as.acc[dt]); as.acc[dt] = MFMA32(a1, p1, as.acc[dt]);
;     }
.Lfast_sel_nr:
	v_fma_f32 v16, v16, s52, -v14
	v_exp_f32_e32 v16, v16
	v_fma_f32 v17, v17, s52, -v14
	v_exp_f32_e32 v17, v17
	v_add_f32_e32 v10, 0, v16
	v_add_f32_e32 v10, v17, v10
	s_waitcnt lgkmcnt(12)
	v_mfma_f32_32x32x16_bf16 v[96:111], v[228:231], v[124:127], v[96:111]
	v_fma_f32 v18, v18, s52, -v14
	v_exp_f32_e32 v18, v18
	v_fma_f32 v19, v19, s52, -v14
	v_exp_f32_e32 v19, v19
	v_add_f32_e32 v10, v18, v10
	v_add_f32_e32 v10, v19, v10
	s_waitcnt lgkmcnt(11)
	v_mfma_f32_32x32x16_bf16 v[96:111], v[232:235], v[128:131], v[96:111]
	v_fma_f32 v20, v20, s52, -v14
	v_exp_f32_e32 v20, v20
	v_fma_f32 v21, v21, s52, -v14
	v_exp_f32_e32 v21, v21
	v_add_f32_e32 v10, v20, v10
	v_add_f32_e32 v10, v21, v10
	s_waitcnt lgkmcnt(10)
	v_mfma_f32_32x32x16_bf16 v[96:111], v[240:243], v[132:135], v[96:111]
	v_fma_f32 v22, v22, s52, -v14
	v_exp_f32_e32 v22, v22
	v_fma_f32 v23, v23, s52, -v14
	v_exp_f32_e32 v23, v23
	v_add_f32_e32 v10, v22, v10
	v_add_f32_e32 v10, v23, v10
	v_cvt_pk_bf16_f32 v2, v16, v17
	v_cvt_pk_bf16_f32 v3, v18, v19
	v_cvt_pk_bf16_f32 v4, v20, v21
	v_cvt_pk_bf16_f32 v5, v22, v23
	s_waitcnt lgkmcnt(9)
	v_mfma_f32_32x32x16_bf16 v[96:111], v[244:247], v[136:139], v[96:111]
	s_waitcnt lgkmcnt(4)
	v_mfma_f32_32x32x16_bf16 v[64:79], v[184:187], v[2:5], v[64:79]
	v_fma_f32 v24, v24, s52, -v14
	v_exp_f32_e32 v24, v24
	v_fma_f32 v25, v25, s52, -v14
	v_exp_f32_e32 v25, v25
	v_add_f32_e32 v10, v24, v10
	v_add_f32_e32 v10, v25, v10
	v_mfma_f32_32x32x16_bf16 v[80:95], v[180:183], v[2:5], v[80:95]
	ds_read_b64 v[198:199], v255 offset:8192
	ds_read_b64 v[200:201], v214 offset:8192
	ds_read_b64 v[202:203], v255 offset:10240
	ds_read_b64 v[204:205], v214 offset:10240
	ds_read_b64 v[206:207], v255 offset:12288
	ds_read_b64 v[208:209], v214 offset:12288
	ds_read_b64 v[210:211], v255 offset:14336
	ds_read_b64 v[212:213], v214 offset:14336
	v_fma_f32 v26, v26, s52, -v14
	v_exp_f32_e32 v26, v26
	v_fma_f32 v27, v27, s52, -v14
	v_exp_f32_e32 v27, v27
	v_add_f32_e32 v10, v26, v10
	v_add_f32_e32 v10, v27, v10
	s_waitcnt lgkmcnt(10)
	v_mfma_f32_32x32x16_bf16 v[48:63], v[188:191], v[2:5], v[48:63]
	v_fma_f32 v28, v28, s52, -v14
	v_exp_f32_e32 v28, v28
	v_fma_f32 v29, v29, s52, -v14
	v_exp_f32_e32 v29, v29
	v_add_f32_e32 v10, v28, v10
	v_add_f32_e32 v10, v29, v10
	s_waitcnt lgkmcnt(8)
	v_mfma_f32_32x32x16_bf16 v[32:47], v[192:195], v[2:5], v[32:47]
	v_fma_f32 v30, v30, s52, -v14
	v_exp_f32_e32 v30, v30
	v_fma_f32 v31, v31, s52, -v14
	v_exp_f32_e32 v31, v31
	v_add_f32_e32 v10, v30, v10
	v_add_f32_e32 v10, v31, v10
	v_mov_b32_e32 v11, v10
	v_cvt_pk_bf16_f32 v6, v24, v25
	v_cvt_pk_bf16_f32 v7, v26, v27
	v_cvt_pk_bf16_f32 v8, v28, v29
	v_cvt_pk_bf16_f32 v9, v30, v31
	v_mfma_f32_32x32x16_bf16 v[16:31], v[248:251], v[140:143], v[96:111]
	v_permlane32_swap_b32_e32 v10, v11
	v_add_f32_e32 v10, v10, v11
	v_add_f32_e32 v163, v10, v163
	s_waitcnt lgkmcnt(4)
	v_mfma_f32_32x32x16_bf16 v[64:79], v[202:205], v[6:9], v[64:79]
	v_mfma_f32_32x32x16_bf16 v[80:95], v[198:201], v[6:9], v[80:95]
	s_waitcnt lgkmcnt(2)
	v_mfma_f32_32x32x16_bf16 v[48:63], v[206:209], v[6:9], v[48:63]
	s_waitcnt lgkmcnt(0)
	v_mfma_f32_32x32x16_bf16 v[32:47], v[210:213], v[6:9], v[32:47]
	v_and_b32_e32 v0, s41, v144
	v_cmp_ne_u32_e32 vcc, 0, v0
	s_nop 0
	s_mov_b64 s[26:27], vcc
	s_branch .LBB0_556

; #define LAS __attribute__((address_space(3)))
; DI float xh_sum(float x) { const unsigned u = __float_as_uint(x); const auto r = __builtin_amdgcn_permlane32_swap(u, u, false, false); return __uint_as_float(r[0]) + __uint_as_float(r[1]); }
; #define MFMA32(a, b, c) __builtin_amdgcn_mfma_f32_32x32x16_bf16((a), (b), (c), 0, 0, 0)
; DI bf16x8 cat44(s16x4 a, s16x4 b) { return __builtin_shufflevector(a, b, 0, 1, 2, 3, 4, 5, 6, 7); }
; template <int MODE>
; DI void co_finish(f32x16 S, LAS unsigned char* st, int key_base, AttnState& as, int tq, bool rowsel, int vb_in, int hh) {
;     ...
;     const float mxs = mx * SM_SCALE; const bool need = mxs > as.m + 8.f;
;     const float mnew = need ? mxs : as.m, muse = -fmaxf(mnew, -1e20f); float ps = 0.f;
; #pragma unroll
;     for (int i = 0; i < 16; ++i) { const float p = __builtin_amdgcn_exp2f(__builtin_fmaf(S[i], SM_SCALE, muse)); S[i] = p; ps += p; }
;     ps = xh_sum(ps);
;     if (__builtin_amdgcn_ballot_w64(need) != 0ull) {
;         const float alpha = __builtin_amdgcn_exp2f(as.m - mnew);
;         as.l *= alpha;
; #pragma unroll
;         for (int dt = 0; dt < 4; ++dt)
; #pragma unroll
;             for (int i = 0; i < 16; ++i) as.acc[dt][i] *= alpha;
;     }
;     as.l += ps; as.m = mnew;
;     const bf16x8 p0 = pack8(S, 0), p1 = pack8(S, 1);
;     __builtin_amdgcn_s_setprio(1);
; #pragma unroll
;     for (int dt = 0; dt < 4; ++dt) {
;         LAS unsigned char* vp = st + 2048 * dt;
;         const bf16x8 a0 = cat44(*(const LAS s16x4*)(vp + (vb ^ 0)), *(const LAS s16x4*)(vp + (vb ^ 16))), a1 = cat44(*(const LAS s16x4*)(vp + (vb ^ 32)), *(const LAS s16x4*)(vp + (vb ^ 48)));
;         as.acc[dt] = MFMA32(a0, p0, as.acc[dt]); as.acc[dt] = MFMA32(a1, p1, as.acc[dt]);
;     }
.Lfast_win_nr:
	v_fma_f32 v16, v16, s52, -v14
	v_exp_f32_e32 v16, v16
	v_fma_f32 v17, v17, s52, -v14
	v_exp_f32_e32 v17, v17
	v_add_f32_e32 v10, 0, v16
	v_add_f32_e32 v10, v17, v10
	s_waitcnt lgkmcnt(12)
	v_mfma_f32_32x32x16_bf16 v[96:111], v[228:231], v[124:127], v[96:111]
	v_fma_f32 v18, v18, s52, -v14
	v_exp_f32_e32 v18, v18
	v_fma_f32 v19, v19, s52, -v14
	v_exp_f32_e32 v19, v19
	v_add_f32_e32 v10, v18, v10
	v_add_f32_e32 v10, v19, v10
	s_waitcnt lgkmcnt(11)
	v_mfma_f32_32x32x16_bf16 v[96:111], v[232:235], v[128:131], v[96:111]
	v_fma_f32 v20, v20, s52, -v14
	v_exp_f32_e32 v20, v20
	v_fma_f32 v21, v21, s52, -v14
	v_exp_f32_e32 v21, v21
	v_add_f32_e32 v10, v20, v10
	v_add_f32_e32 v10, v21, v10
	s_waitcnt lgkmcnt(10)
	v_mfma_f32_32x32x16_bf16 v[96:111], v[240:243], v[132:135], v[96:111]
	v_fma_f32 v22, v22, s52, -v14
	v_exp_f32_e32 v22, v22
	v_fma_f32 v23, v23, s52, -v14
	v_exp_f32_e32 v23, v23
	v_add_f32_e32 v10, v22, v10
	v_add_f32_e32 v10, v23, v10
	v_cvt_pk_bf16_f32 v2, v16, v17
	v_cvt_pk_bf16_f32 v3, v18, v19
	v_cvt_pk_bf16_f32 v4, v20, v21
	v_cvt_pk_bf16_f32 v5, v22, v23
	s_waitcnt lgkmcnt(9)
	v_mfma_f32_32x32x16_bf16 v[96:111], v[244:247], v[136:139], v[96:111]
	s_waitcnt lgkmcnt(4)
	v_mfma_f32_32x32x16_bf16 v[64:79], v[184:187], v[2:5], v[64:79]
	v_fma_f32 v24, v24, s52, -v14
	v_exp_f32_e32 v24, v24
	v_fma_f32 v25, v25, s52, -v14
	v_exp_f32_e32 v25, v25
	v_add_f32_e32 v10, v24, v10
	v_add_f32_e32 v10, v25, v10
	v_mfma_f32_32x32x16_bf16 v[80:95], v[180:183], v[2:5], v[80:95]
	ds_read_b64 v[198:199], v255 offset:8192
	ds_read_b64 v[200:201], v214 offset:8192
	ds_read_b64 v[202:203], v255 offset:10240
	ds_read_b64 v[204:205], v214 offset:10240
	ds_read_b64 v[206:207], v255 offset:12288
	ds_read_b64 v[208:209], v214 offset:12288
	ds_read_b64 v[210:211], v255 offset:14336
	ds_read_b64 v[212:213], v214 offset:14336
	v_fma_f32 v26, v26, s52, -v14
	v_exp_f32_e32 v26, v26
	v_fma_f32 v27, v27, s52, -v14
	v_exp_f32_e32 v27, v27
	v_add_f32_e32 v10, v26, v10
	v_add_f32_e32 v10, v27, v10
	s_waitcnt lgkmcnt(10)
	v_mfma_f32_32x32x16_bf16 v[48:63], v[188:191], v[2:5], v[48:63]
	v_fma_f32 v28, v28, s52, -v14
	v_exp_f32_e32 v28, v28
	v_fma_f32 v29, v29, s52, -v14
	v_exp_f32_e32 v29, v29
	v_add_f32_e32 v10, v28, v10
	v_add_f32_e32 v10, v29, v10
	s_waitcnt lgkmcnt(8)
	v_mfma_f32_32x32x16_bf16 v[32:47], v[192:195], v[2:5], v[32:47]
	v_fma_f32 v30, v30, s52, -v14
	v_exp_f32_e32 v30, v30
	v_fma_f32 v31, v31, s52, -v14
	v_exp_f32_e32 v31, v31
	v_add_f32_e32 v10, v30, v10
	v_add_f32_e32 v10, v31, v10
	v_mov_b32_e32 v11, v10
	v_cvt_pk_bf16_f32 v6, v24, v25
	v_cvt_pk_bf16_f32 v7, v26, v27
	v_cvt_pk_bf16_f32 v8, v28, v29
	v_cvt_pk_bf16_f32 v9, v30, v31
	v_mfma_f32_32x32x16_bf16 v[16:31], v[248:251], v[140:143], v[96:111]
	v_permlane32_swap_b32_e32 v10, v11
	v_add_f32_e32 v10, v10, v11
	v_add_f32_e32 v175, v10, v175
	s_waitcnt lgkmcnt(4)
	v_mfma_f32_32x32x16_bf16 v[64:79], v[202:205], v[6:9], v[64:79]
	v_mfma_f32_32x32x16_bf16 v[80:95], v[198:201], v[6:9], v[80:95]
	s_waitcnt lgkmcnt(2)
	v_mfma_f32_32x32x16_bf16 v[48:63], v[206:209], v[6:9], v[48:63]
	s_waitcnt lgkmcnt(0)
	v_mfma_f32_32x32x16_bf16 v[32:47], v[210:213], v[6:9], v[32:47]
	s_mov_b64 s[26:27], -1
	s_mov_b32 s62, s16
	s_mov_b32 s64, s68
	s_branch .LBB0_523
